# residual GEMM K-loop: last 12 VALU per iteration removed (LDS read bases precomputed per tile, LDS-DMA addresses via SGPR base s[100:101])
# speedup vs baseline: 1.0084x; 1.0009x over previous
; template <class Epi, class Sched, bool ALIGN_EPI = false, bool SP2 = false>
; __device__ __forceinline__ void gemm_phase(PG8_LAS unsigned char* lds, const Gemm g, const Sched& S, const Epi& E) {
;     ...
;     f32x4 acc[2][2][4][2];
; #pragma unroll
;     for (int a = 0; a < 2; ++a)
; #pragma unroll
;         for (int b = 0; b < 2; ++b)
; #pragma unroll
;             for (int m = 0; m < 4; ++m)
; #pragma unroll
;                 for (int n = 0; n < 2; ++n) acc[a][b][m][n] = (f32x4){0.f, 0.f, 0.f, 0.f};
.LBB0_344:
	s_add_u32 s58, s42, 0x100
	v_mov_b32_e32 v0, 0
	s_addc_u32 s59, s43, 0
	s_mov_b32 s10, 0
	v_mov_b32_e32 v1, v0
	v_mov_b32_e32 v2, v0
	v_mov_b32_e32 v3, v0
	v_mov_b32_e32 v4, v0
	v_mov_b32_e32 v5, v0
	v_mov_b32_e32 v6, v0
	v_mov_b32_e32 v7, v0
	v_mov_b32_e32 v16, v0
	v_mov_b32_e32 v17, v0
	v_mov_b32_e32 v18, v0
	v_mov_b32_e32 v19, v0
	v_mov_b32_e32 v20, v0
	v_mov_b32_e32 v21, v0
	s_waitcnt lgkmcnt(0)
	v_mov_b32_e32 v22, v0
	v_mov_b32_e32 v23, v0
	v_mov_b32_e32 v32, v0
	v_mov_b32_e32 v33, v0
	v_mov_b32_e32 v34, v0
	v_mov_b32_e32 v35, v0
	v_mov_b32_e32 v36, v0
	v_mov_b32_e32 v37, v0
	v_mov_b32_e32 v38, v0
	v_mov_b32_e32 v39, v0
	v_mov_b32_e32 v48, v0
	v_mov_b32_e32 v49, v0
	v_mov_b32_e32 v50, v0
	v_mov_b32_e32 v51, v0
	v_mov_b32_e32 v52, v0
	v_mov_b32_e32 v53, v0
	v_mov_b32_e32 v54, v0
	v_mov_b32_e32 v55, v0
	v_mov_b32_e32 v8, v0
	v_mov_b32_e32 v9, v0
	v_mov_b32_e32 v10, v0
	v_mov_b32_e32 v11, v0
	v_mov_b32_e32 v12, v0
	v_mov_b32_e32 v13, v0
	v_mov_b32_e32 v14, v0
	v_mov_b32_e32 v15, v0
	v_mov_b32_e32 v24, v0
	v_mov_b32_e32 v25, v0
	v_mov_b32_e32 v26, v0
	v_mov_b32_e32 v27, v0
	v_mov_b32_e32 v28, v0
	v_mov_b32_e32 v29, v0
	v_mov_b32_e32 v30, v0
	v_mov_b32_e32 v31, v0
	v_mov_b32_e32 v40, v0
	v_mov_b32_e32 v41, v0
	v_mov_b32_e32 v42, v0
	v_mov_b32_e32 v43, v0
	v_mov_b32_e32 v44, v0
	v_mov_b32_e32 v45, v0
	v_mov_b32_e32 v46, v0
	v_mov_b32_e32 v47, v0
	v_mov_b32_e32 v56, v0
	v_mov_b32_e32 v57, v0
	v_mov_b32_e32 v58, v0
	v_mov_b32_e32 v59, v0
	v_mov_b32_e32 v60, v0
	v_mov_b32_e32 v61, v0
	v_mov_b32_e32 v62, v0
	v_mov_b32_e32 v63, v0
	v_mov_b32_e32 v64, v0
	v_mov_b32_e32 v65, v0
	v_mov_b32_e32 v66, v0
	v_mov_b32_e32 v67, v0
	v_mov_b32_e32 v68, v0
	v_mov_b32_e32 v69, v0
	v_mov_b32_e32 v70, v0
	v_mov_b32_e32 v71, v0
	v_mov_b32_e32 v80, v0
	v_mov_b32_e32 v81, v0
	v_mov_b32_e32 v82, v0
	v_mov_b32_e32 v83, v0
	v_mov_b32_e32 v84, v0
	v_mov_b32_e32 v85, v0
	v_mov_b32_e32 v86, v0
	v_mov_b32_e32 v87, v0
	v_mov_b32_e32 v98, v0
	v_mov_b32_e32 v99, v0
	v_mov_b32_e32 v100, v0
	v_mov_b32_e32 v101, v0
	v_mov_b32_e32 v102, v0
	v_mov_b32_e32 v103, v0
	v_mov_b32_e32 v104, v0
	v_mov_b32_e32 v105, v0
	v_mov_b32_e32 v114, v0
	v_mov_b32_e32 v115, v0
	v_mov_b32_e32 v116, v0
	v_mov_b32_e32 v117, v0
	v_mov_b32_e32 v118, v0
	v_mov_b32_e32 v119, v0
	v_mov_b32_e32 v120, v0
	v_mov_b32_e32 v121, v0
	v_mov_b32_e32 v72, v0
	v_mov_b32_e32 v73, v0
	v_mov_b32_e32 v74, v0
	v_mov_b32_e32 v75, v0
	v_mov_b32_e32 v76, v0
	v_mov_b32_e32 v77, v0
	v_mov_b32_e32 v78, v0
	v_mov_b32_e32 v79, v0
	v_mov_b32_e32 v88, v0
	v_mov_b32_e32 v89, v0
	v_mov_b32_e32 v90, v0
	v_mov_b32_e32 v91, v0
	v_mov_b32_e32 v92, v0
	v_mov_b32_e32 v93, v0
	v_mov_b32_e32 v94, v0
	v_mov_b32_e32 v95, v0
	v_mov_b32_e32 v106, v0
	v_mov_b32_e32 v107, v0
	v_mov_b32_e32 v108, v0
	v_mov_b32_e32 v109, v0
	v_mov_b32_e32 v110, v0
	v_mov_b32_e32 v111, v0
	v_mov_b32_e32 v112, v0
	v_mov_b32_e32 v113, v0
	v_mov_b32_e32 v130, v0
	v_mov_b32_e32 v131, v0
	v_mov_b32_e32 v132, v0
	v_mov_b32_e32 v133, v0
	v_mov_b32_e32 v134, v0
	v_mov_b32_e32 v135, v0
	v_mov_b32_e32 v136, v0
	v_mov_b32_e32 v137, v0
	v_add_u32_e32 v218, 0x10000, v97
	v_add_u32_e32 v219, 0x14000, v97
	v_add_u32_e32 v220, 0x18000, v97
	v_add_u32_e32 v221, 0x1c000, v97
	s_branch .LBB0_346
.LBB0_345:
	s_add_i32 s10, s10, 2
	s_add_u32 s44, s42, s34
	s_addc_u32 s45, s43, s35
	s_add_i32 s18, 0, 0x10000
	s_and_b64 s[2:3], exec, s[46:47]
	s_cselect_b32 s3, s13, s59
	s_cselect_b32 s2, s12, s58
	s_add_i32 s38, 0, 0x14000
	ds_read_b128 v[122:125], v218
	ds_read_b128 v[126:129], v218 offset:1024
	ds_read_b128 v[138:141], v218 offset:2048
	ds_read_b128 v[142:145], v218 offset:3072
	ds_read_b128 v[146:149], v219
	ds_read_b128 v[150:153], v219 offset:1024
	ds_read_b128 v[154:157], v219 offset:2048
	ds_read_b128 v[170:173], v219 offset:3072
	s_add_i32 m0, s97, 0xc000
	ds_read_b128 v[174:177], v188
	ds_read_b128 v[180:183], v188 offset:1024
	ds_read_b128 v[184:187], v188 offset:2048
	ds_read_b128 v[190:193], v188 offset:3072
	ds_read_b128 v[194:197], v188 offset:4096
	ds_read_b128 v[198:201], v188 offset:5120
	ds_read_b128 v[202:205], v188 offset:6144
	ds_read_b128 v[206:209], v188 offset:7168
	global_load_lds_dwordx4 v168, s[24:25]
	s_add_i32 m0, s97, 0xe000
	s_nop 0
	global_load_lds_dwordx4 v166, s[24:25]
	s_waitcnt vmcnt(8)
	s_waitcnt lgkmcnt(0)
	s_barrier
	v_mfma_f32_16x16x32_bf16 v[134:137], v[122:125], v[174:177], v[134:137]
	v_mfma_f32_16x16x32_bf16 v[130:133], v[138:141], v[174:177], v[130:133]
	v_mfma_f32_16x16x32_bf16 v[106:109], v[138:141], v[184:187], v[106:109]
	v_mfma_f32_16x16x32_bf16 v[110:113], v[122:125], v[184:187], v[110:113]
	v_mfma_f32_16x16x32_bf16 v[92:95], v[122:125], v[194:197], v[92:95]
	v_mfma_f32_16x16x32_bf16 v[88:91], v[138:141], v[194:197], v[88:91]
	v_mfma_f32_16x16x32_bf16 v[72:75], v[138:141], v[202:205], v[72:75]
	v_mfma_f32_16x16x32_bf16 v[76:79], v[122:125], v[202:205], v[76:79]
	v_mfma_f32_16x16x32_bf16 v[134:137], v[126:129], v[180:183], v[134:137]
	v_mfma_f32_16x16x32_bf16 v[130:133], v[142:145], v[180:183], v[130:133]
	v_mfma_f32_16x16x32_bf16 v[106:109], v[142:145], v[190:193], v[106:109]
	v_mfma_f32_16x16x32_bf16 v[110:113], v[126:129], v[190:193], v[110:113]
	v_mfma_f32_16x16x32_bf16 v[92:95], v[126:129], v[198:201], v[92:95]
	v_mfma_f32_16x16x32_bf16 v[88:91], v[142:145], v[198:201], v[88:91]
	v_mfma_f32_16x16x32_bf16 v[72:75], v[142:145], v[206:209], v[72:75]
	v_mfma_f32_16x16x32_bf16 v[76:79], v[126:129], v[206:209], v[76:79]
	v_mfma_f32_16x16x32_bf16 v[118:121], v[146:149], v[174:177], v[118:121]
	v_mfma_f32_16x16x32_bf16 v[114:117], v[154:157], v[174:177], v[114:117]
	v_mfma_f32_16x16x32_bf16 v[98:101], v[154:157], v[184:187], v[98:101]
	v_mfma_f32_16x16x32_bf16 v[102:105], v[146:149], v[184:187], v[102:105]
	v_mfma_f32_16x16x32_bf16 v[84:87], v[146:149], v[194:197], v[84:87]
	v_mfma_f32_16x16x32_bf16 v[80:83], v[154:157], v[194:197], v[80:83]
	v_mfma_f32_16x16x32_bf16 v[64:67], v[154:157], v[202:205], v[64:67]
	v_mfma_f32_16x16x32_bf16 v[68:71], v[146:149], v[202:205], v[68:71]
	v_mfma_f32_16x16x32_bf16 v[118:121], v[150:153], v[180:183], v[118:121]
	v_mfma_f32_16x16x32_bf16 v[114:117], v[170:173], v[180:183], v[114:117]
	v_mfma_f32_16x16x32_bf16 v[98:101], v[170:173], v[190:193], v[98:101]
	v_mfma_f32_16x16x32_bf16 v[102:105], v[150:153], v[190:193], v[102:105]
	v_mfma_f32_16x16x32_bf16 v[84:87], v[150:153], v[198:201], v[84:87]
	v_mfma_f32_16x16x32_bf16 v[80:83], v[170:173], v[198:201], v[80:83]
	v_mfma_f32_16x16x32_bf16 v[64:67], v[170:173], v[206:209], v[64:67]
	v_mfma_f32_16x16x32_bf16 v[68:71], v[150:153], v[206:209], v[68:71]
	s_barrier
	s_add_i32 s18, s18, s96
	s_add_u32 s100, s2, s36
	s_mov_b32 m0, s18
	s_addc_u32 s101, s3, s37
	ds_read_b128 v[174:177], v188 offset:16384
	ds_read_b128 v[180:183], v188 offset:17408
	ds_read_b128 v[184:187], v188 offset:18432
	ds_read_b128 v[190:193], v188 offset:19456
	ds_read_b128 v[194:197], v188 offset:20480
	ds_read_b128 v[198:201], v188 offset:21504
	ds_read_b128 v[202:205], v188 offset:22528
	ds_read_b128 v[206:209], v188 offset:23552
	global_load_lds_dwordx4 v162, s[2:3]
	s_add_i32 m0, s18, 0x2000
	s_nop 0
	global_load_lds_dwordx4 v158, s[2:3]
	s_add_u32 s2, s2, s48
	s_addc_u32 s3, s3, 0
	s_add_i32 s18, s38, s96
	s_mov_b32 m0, s18
	s_nop 0
	global_load_lds_dwordx4 v162, s[2:3]
	s_add_i32 m0, s18, 0x2000
	s_nop 0
	global_load_lds_dwordx4 v158, s[2:3]
	s_mov_b32 m0, s97
	s_nop 0
	global_load_lds_dwordx4 v164, s[42:43]
	s_mov_b32 m0, s22
	s_nop 0
	global_load_lds_dwordx4 v160, s[42:43]
	s_waitcnt vmcnt(8)
	s_waitcnt lgkmcnt(0)
	s_barrier
	v_mfma_f32_16x16x32_bf16 v[60:63], v[122:125], v[174:177], v[60:63]
	v_mfma_f32_16x16x32_bf16 v[56:59], v[138:141], v[174:177], v[56:59]
	v_mfma_f32_16x16x32_bf16 v[40:43], v[138:141], v[184:187], v[40:43]
	v_mfma_f32_16x16x32_bf16 v[44:47], v[122:125], v[184:187], v[44:47]
	v_mfma_f32_16x16x32_bf16 v[28:31], v[122:125], v[194:197], v[28:31]
	v_mfma_f32_16x16x32_bf16 v[24:27], v[138:141], v[194:197], v[24:27]
	v_mfma_f32_16x16x32_bf16 v[8:11], v[138:141], v[202:205], v[8:11]
	v_mfma_f32_16x16x32_bf16 v[12:15], v[122:125], v[202:205], v[12:15]
	v_mfma_f32_16x16x32_bf16 v[60:63], v[126:129], v[180:183], v[60:63]
	v_mfma_f32_16x16x32_bf16 v[56:59], v[142:145], v[180:183], v[56:59]
	v_mfma_f32_16x16x32_bf16 v[40:43], v[142:145], v[190:193], v[40:43]
	v_mfma_f32_16x16x32_bf16 v[44:47], v[126:129], v[190:193], v[44:47]
	v_mfma_f32_16x16x32_bf16 v[28:31], v[126:129], v[198:201], v[28:31]
	v_mfma_f32_16x16x32_bf16 v[24:27], v[142:145], v[198:201], v[24:27]
	v_mfma_f32_16x16x32_bf16 v[8:11], v[142:145], v[206:209], v[8:11]
	v_mfma_f32_16x16x32_bf16 v[12:15], v[126:129], v[206:209], v[12:15]
	v_mfma_f32_16x16x32_bf16 v[52:55], v[146:149], v[174:177], v[52:55]
	v_mfma_f32_16x16x32_bf16 v[48:51], v[154:157], v[174:177], v[48:51]
	v_mfma_f32_16x16x32_bf16 v[32:35], v[154:157], v[184:187], v[32:35]
	v_mfma_f32_16x16x32_bf16 v[36:39], v[146:149], v[184:187], v[36:39]
	v_mfma_f32_16x16x32_bf16 v[20:23], v[146:149], v[194:197], v[20:23]
	v_mfma_f32_16x16x32_bf16 v[16:19], v[154:157], v[194:197], v[16:19]
	v_mfma_f32_16x16x32_bf16 v[0:3], v[154:157], v[202:205], v[0:3]
	v_mfma_f32_16x16x32_bf16 v[4:7], v[146:149], v[202:205], v[4:7]
	v_mfma_f32_16x16x32_bf16 v[52:55], v[150:153], v[180:183], v[52:55]
	v_mfma_f32_16x16x32_bf16 v[48:51], v[170:173], v[180:183], v[48:51]
	v_mfma_f32_16x16x32_bf16 v[32:35], v[170:173], v[190:193], v[32:35]
	v_mfma_f32_16x16x32_bf16 v[36:39], v[150:153], v[190:193], v[36:39]
	v_mfma_f32_16x16x32_bf16 v[20:23], v[150:153], v[198:201], v[20:23]
	v_mfma_f32_16x16x32_bf16 v[16:19], v[170:173], v[198:201], v[16:19]
	v_mfma_f32_16x16x32_bf16 v[0:3], v[170:173], v[206:209], v[0:3]
	v_mfma_f32_16x16x32_bf16 v[4:7], v[150:153], v[206:209], v[4:7]
	s_barrier
	s_add_i32 s18, 0, 0x18000
	s_add_i32 s38, 0, 0x1c000
	ds_read_b128 v[122:125], v220
	ds_read_b128 v[126:129], v220 offset:1024
	ds_read_b128 v[138:141], v220 offset:2048
	ds_read_b128 v[142:145], v220 offset:3072
	ds_read_b128 v[146:149], v221
	ds_read_b128 v[150:153], v221 offset:1024
	ds_read_b128 v[154:157], v221 offset:2048
	ds_read_b128 v[170:173], v221 offset:3072
	s_add_u32 s2, s42, s98
	s_addc_u32 s3, s43, 0
	s_mov_b32 m0, s23
	ds_read_b128 v[174:177], v188 offset:32768
	ds_read_b128 v[180:183], v188 offset:33792
	ds_read_b128 v[184:187], v188 offset:34816
	ds_read_b128 v[190:193], v188 offset:35840
	ds_read_b128 v[194:197], v188 offset:36864
	ds_read_b128 v[198:201], v188 offset:37888
	ds_read_b128 v[202:205], v188 offset:38912
	ds_read_b128 v[206:209], v188 offset:39936
	global_load_lds_dwordx4 v164, s[2:3]
	s_mov_b32 m0, s19
	s_nop 0
	global_load_lds_dwordx4 v160, s[2:3]
	s_waitcnt vmcnt(8)
	s_waitcnt lgkmcnt(0)
	s_barrier
; template <class Epi, class Sched, bool ALIGN_EPI = false, bool SP2 = false>
; __device__ __forceinline__ void gemm_phase(PG8_LAS unsigned char* lds, const Gemm g, const Sched& S, const Epi& E) {
;     ...
;         if constexpr (Epi::PEEL) {
;             const char* a1 = cA + kstepA; const char* a2 = cA + 2 * kstepA; const char* b2 = cB + 2 * kstepB; const char* a3 = a2 + kstepA; const char* b3 = b2 + kstepB;
;             PG8_ITER(8);
;         }
;         for (int t = (Epi::PEEL ? 2 : 0); t < nt; t += 2) {
;             const bool last = (t == nt - 2);
;             const char* a1 = cA + (size_t)(t + 1) * kstepA;
;             const char* a2 = last ? nA : cA + (size_t)(t + 2) * kstepA; const char* b2 = last ? nB : cB + (size_t)(t + 2) * kstepB;
;             const char* a3 = a2 + kstepA; const char* b3 = b2 + kstepB;
;             PG8_ITER(8);
	v_mfma_f32_16x16x32_bf16 v[134:137], v[122:125], v[174:177], v[134:137]
	v_mfma_f32_16x16x32_bf16 v[130:133], v[138:141], v[174:177], v[130:133]
	v_mfma_f32_16x16x32_bf16 v[106:109], v[138:141], v[184:187], v[106:109]
	v_mfma_f32_16x16x32_bf16 v[110:113], v[122:125], v[184:187], v[110:113]
	v_mfma_f32_16x16x32_bf16 v[92:95], v[122:125], v[194:197], v[92:95]
	v_mfma_f32_16x16x32_bf16 v[88:91], v[138:141], v[194:197], v[88:91]
	v_mfma_f32_16x16x32_bf16 v[72:75], v[138:141], v[202:205], v[72:75]
	v_mfma_f32_16x16x32_bf16 v[76:79], v[122:125], v[202:205], v[76:79]
	v_mfma_f32_16x16x32_bf16 v[134:137], v[126:129], v[180:183], v[134:137]
	v_mfma_f32_16x16x32_bf16 v[130:133], v[142:145], v[180:183], v[130:133]
	v_mfma_f32_16x16x32_bf16 v[106:109], v[142:145], v[190:193], v[106:109]
	v_mfma_f32_16x16x32_bf16 v[110:113], v[126:129], v[190:193], v[110:113]
	v_mfma_f32_16x16x32_bf16 v[92:95], v[126:129], v[198:201], v[92:95]
	v_mfma_f32_16x16x32_bf16 v[88:91], v[142:145], v[198:201], v[88:91]
	v_mfma_f32_16x16x32_bf16 v[72:75], v[142:145], v[206:209], v[72:75]
	v_mfma_f32_16x16x32_bf16 v[76:79], v[126:129], v[206:209], v[76:79]
	v_mfma_f32_16x16x32_bf16 v[118:121], v[146:149], v[174:177], v[118:121]
	v_mfma_f32_16x16x32_bf16 v[114:117], v[154:157], v[174:177], v[114:117]
	v_mfma_f32_16x16x32_bf16 v[98:101], v[154:157], v[184:187], v[98:101]
	v_mfma_f32_16x16x32_bf16 v[102:105], v[146:149], v[184:187], v[102:105]
	v_mfma_f32_16x16x32_bf16 v[84:87], v[146:149], v[194:197], v[84:87]
	v_mfma_f32_16x16x32_bf16 v[80:83], v[154:157], v[194:197], v[80:83]
	v_mfma_f32_16x16x32_bf16 v[64:67], v[154:157], v[202:205], v[64:67]
	v_mfma_f32_16x16x32_bf16 v[68:71], v[146:149], v[202:205], v[68:71]
	v_mfma_f32_16x16x32_bf16 v[118:121], v[150:153], v[180:183], v[118:121]
	v_mfma_f32_16x16x32_bf16 v[114:117], v[170:173], v[180:183], v[114:117]
	v_mfma_f32_16x16x32_bf16 v[98:101], v[170:173], v[190:193], v[98:101]
	v_mfma_f32_16x16x32_bf16 v[102:105], v[150:153], v[190:193], v[102:105]
	v_mfma_f32_16x16x32_bf16 v[84:87], v[150:153], v[198:201], v[84:87]
	v_mfma_f32_16x16x32_bf16 v[80:83], v[170:173], v[198:201], v[80:83]
	v_mfma_f32_16x16x32_bf16 v[64:67], v[170:173], v[206:209], v[64:67]
	v_mfma_f32_16x16x32_bf16 v[68:71], v[150:153], v[206:209], v[68:71]
	s_barrier
	s_add_i32 s2, s18, s96
	s_mov_b32 m0, s2
	ds_read_b128 v[174:177], v188 offset:49152
	ds_read_b128 v[180:183], v188 offset:50176
	ds_read_b128 v[184:187], v188 offset:51200
	ds_read_b128 v[190:193], v188 offset:52224
	ds_read_b128 v[194:197], v188 offset:53248
	ds_read_b128 v[198:201], v188 offset:54272
	ds_read_b128 v[202:205], v188 offset:55296
	ds_read_b128 v[206:209], v188 offset:56320
	global_load_lds_dwordx4 v162, s[100:101]
	s_add_i32 m0, s2, 0x2000
	s_add_i32 s2, s38, s96
	global_load_lds_dwordx4 v158, s[100:101]
	s_add_u32 s100, s100, s48
	s_addc_u32 s101, s101, 0
	s_mov_b32 m0, s2
	s_nop 0
	global_load_lds_dwordx4 v162, s[100:101]
	s_add_i32 m0, s2, 0x2000
	s_nop 0
	global_load_lds_dwordx4 v158, s[100:101]
	s_mov_b32 m0, s6
	s_nop 0
	global_load_lds_dwordx4 v164, s[44:45]
	s_mov_b32 m0, s56
	s_nop 0
	global_load_lds_dwordx4 v160, s[44:45]
	s_waitcnt vmcnt(8)
	s_waitcnt lgkmcnt(0)
	s_barrier
	v_mfma_f32_16x16x32_bf16 v[60:63], v[122:125], v[174:177], v[60:63]
	v_mfma_f32_16x16x32_bf16 v[56:59], v[138:141], v[174:177], v[56:59]
	v_mfma_f32_16x16x32_bf16 v[40:43], v[138:141], v[184:187], v[40:43]
	v_mfma_f32_16x16x32_bf16 v[44:47], v[122:125], v[184:187], v[44:47]
	v_mfma_f32_16x16x32_bf16 v[28:31], v[122:125], v[194:197], v[28:31]
	v_mfma_f32_16x16x32_bf16 v[24:27], v[138:141], v[194:197], v[24:27]
	v_mfma_f32_16x16x32_bf16 v[8:11], v[138:141], v[202:205], v[8:11]
	v_mfma_f32_16x16x32_bf16 v[12:15], v[122:125], v[202:205], v[12:15]
	v_mfma_f32_16x16x32_bf16 v[60:63], v[126:129], v[180:183], v[60:63]
	v_mfma_f32_16x16x32_bf16 v[56:59], v[142:145], v[180:183], v[56:59]
	v_mfma_f32_16x16x32_bf16 v[40:43], v[142:145], v[190:193], v[40:43]
	v_mfma_f32_16x16x32_bf16 v[44:47], v[126:129], v[190:193], v[44:47]
	v_mfma_f32_16x16x32_bf16 v[28:31], v[126:129], v[198:201], v[28:31]
	v_mfma_f32_16x16x32_bf16 v[24:27], v[142:145], v[198:201], v[24:27]
	v_mfma_f32_16x16x32_bf16 v[8:11], v[142:145], v[206:209], v[8:11]
	v_mfma_f32_16x16x32_bf16 v[12:15], v[126:129], v[206:209], v[12:15]
	v_mfma_f32_16x16x32_bf16 v[52:55], v[146:149], v[174:177], v[52:55]
	v_mfma_f32_16x16x32_bf16 v[48:51], v[154:157], v[174:177], v[48:51]
	v_mfma_f32_16x16x32_bf16 v[32:35], v[154:157], v[184:187], v[32:35]
	v_mfma_f32_16x16x32_bf16 v[36:39], v[146:149], v[184:187], v[36:39]
	v_mfma_f32_16x16x32_bf16 v[20:23], v[146:149], v[194:197], v[20:23]
	v_mfma_f32_16x16x32_bf16 v[16:19], v[154:157], v[194:197], v[16:19]
	v_mfma_f32_16x16x32_bf16 v[0:3], v[154:157], v[202:205], v[0:3]
	v_mfma_f32_16x16x32_bf16 v[4:7], v[146:149], v[202:205], v[4:7]
	v_mfma_f32_16x16x32_bf16 v[52:55], v[150:153], v[180:183], v[52:55]
	v_mfma_f32_16x16x32_bf16 v[48:51], v[170:173], v[180:183], v[48:51]
	v_mfma_f32_16x16x32_bf16 v[32:35], v[170:173], v[190:193], v[32:35]
	v_mfma_f32_16x16x32_bf16 v[36:39], v[150:153], v[190:193], v[36:39]
	v_mfma_f32_16x16x32_bf16 v[20:23], v[150:153], v[198:201], v[20:23]
	v_mfma_f32_16x16x32_bf16 v[16:19], v[170:173], v[198:201], v[16:19]
	v_mfma_f32_16x16x32_bf16 v[0:3], v[170:173], v[206:209], v[0:3]
	v_mfma_f32_16x16x32_bf16 v[4:7], v[150:153], v[206:209], v[4:7]
	s_barrier
	s_add_u32 s58, s58, 0x100
	s_addc_u32 s59, s59, 0
	s_add_u32 s24, s24, s49
	s_addc_u32 s25, s25, 0
	s_cmp_ge_u32 s10, s8
	s_cbranch_scc1 .LBB0_348
